# M2 roles: one DeltaNet scan slice per CU (blocks 0..31), mLSTM a2 units on their sibling halves, attention and weight conversion on blocks 32..255
# speedup vs baseline: 1.2674x; 1.0036x over previous
; DI void phase_m2(const Params& p, int l, int bid, int nb, h16* lds) {
;   asm volatile("" : "+v"(bid));
;   const int nA = conv_total(l) - 2560;
;   const int nB = (l + 1 < 4) ? 2560 : 0;
;   const int total = 32 + 136 + 2048 + 3072 + nA + nB;
;   if (l & 1) moe_reset(p, bid, nb);
;   const int ustart = (bid < 32) ? bid : bid;
;   const int ustep = (bid < 32) ? total : (nb - 32);
;   for (int u = ustart; u < total; u += ustep) {
;     int v = u;
;     if (v >= 5288) { v -= 5288; if (v < nA) conv_one(p, l, 2560 + v, lds); else conv_one(p, l + 1, v - nA, lds); continue; }
.LBB0_892:
	s_and_b64 s[2:3], exec, s[2:3]
	s_movk_i32 s2, 0x2700
	s_cselect_b32 s91, s2, 0x5880
	v_readlane_b32 s2, v255, 30
	v_readlane_b32 s4, v255, 32
	v_readlane_b32 s3, v255, 31
	s_add_i32 s2, s4, 1
	v_readlane_b32 s5, v255, 33
	v_writelane_b32 v255, s2, 30
	s_cmp_lg_u32 s4, 3
	s_nop 0
	v_writelane_b32 v255, s3, 31
	s_cselect_b64 s[2:3], -1, 0
	v_writelane_b32 v255, s2, 36
	s_cmp_eq_u32 s4, 3
	s_nop 0
	v_writelane_b32 v255, s3, 37
	s_movk_i32 s2, 0xaa8
	s_cselect_b32 s2, s2, 0x14a8
	s_add_i32 s90, s91, s2
	v_cmp_gt_i32_e32 vcc, s90, v1
	s_and_saveexec_b64 s[64:65], vcc
	s_cbranch_execz .LBB0_1028
	v_readlane_b32 s16, v255, 32
	v_readlane_b32 s68, v255, 30
	v_readlane_b32 s2, v254, 31
	v_readlane_b32 s17, v255, 33
	v_readlane_b32 s69, v255, 31
	v_mov_b32_e32 v2, s2
	s_lshr_b32 s2, s68, 1
	s_mov_b32 s17, s69
	s_lshr_b32 s4, s16, 1
	v_readlane_b32 s36, v252, 11
	s_addk_i32 s91, 0xf600
	s_lshl_b32 s92, s16, 3
	s_mul_hi_u32 s6, s68, 0x2420000
	s_mul_i32 s7, s68, 0x2420000
	s_mul_i32 s66, s2, 0xb00000
	s_lshl_b32 s93, s2, 3
	s_lshl_b64 s[2:3], s[68:69], 22
	s_lshl_b32 s94, s4, 3
	s_mul_i32 s68, s4, 0xb00000
	s_lshl_b64 s[4:5], s[16:17], 22
	v_readlane_b32 s38, v252, 13
	v_readlane_b32 s48, v252, 23
	v_readlane_b32 s49, v252, 24
	v_readlane_b32 s50, v252, 25
	v_readlane_b32 s51, v252, 26
	v_readlane_b32 s39, v252, 14
	s_add_u32 s70, s38, s7
	v_readlane_b32 s48, v252, 43
	v_readlane_b32 s40, v252, 15
	v_readlane_b32 s41, v252, 16
	v_readlane_b32 s42, v252, 17
	v_readlane_b32 s43, v252, 18
	v_readlane_b32 s44, v252, 19
	v_readlane_b32 s45, v252, 20
	v_readlane_b32 s46, v252, 21
	v_readlane_b32 s47, v252, 22
	s_addc_u32 s71, s39, s6
	v_readlane_b32 s49, v252, 44
	v_readlane_b32 s50, v252, 45
	v_readlane_b32 s51, v252, 46
	v_readlane_b32 s52, v252, 47
	v_readlane_b32 s53, v252, 48
	v_readlane_b32 s54, v252, 49
	v_readlane_b32 s55, v252, 50
	v_readlane_b32 s56, v252, 51
	v_readlane_b32 s57, v252, 52
	s_add_u32 s72, s56, s66
	v_readlane_b32 s40, v252, 27
	s_addc_u32 s73, s57, 0
	v_readlane_b32 s50, v252, 37
	v_readlane_b32 s51, v252, 38
	s_add_u32 s74, s50, s2
	s_addc_u32 s75, s51, s3
	s_add_u32 s76, s56, s68
	s_addc_u32 s77, s57, 0
	s_add_u32 s78, s50, s4
	v_mov_b32_e32 v3, s90
	v_cmp_gt_i32_e32 vcc, 32, v1
	s_mul_hi_u32 s8, s16, 0x2420000
	v_writelane_b32 v255, s16, 32
	s_mul_i32 s9, s16, 0x2420000
	s_addc_u32 s79, s51, s5
	v_cndmask_b32_e32 v161, v2, v3, vcc
	s_add_u32 s80, s38, s9
	s_mov_b32 s67, s69
	v_writelane_b32 v255, s17, 33
	s_addc_u32 s81, s39, s8
	v_lshlrev_b32_e32 v162, 3, v1
	v_lshlrev_b32_e32 v163, 3, v161
	v_lshlrev_b32_e32 v164, 10, v1
	v_lshlrev_b32_e32 v165, 10, v161
	v_lshrrev_b32_e32 v162, 1, v181
	v_and_b32_e32 v163, 1, v181
	v_add_u32_e32 v1, 0x68, v181
	v_mov_b32_e32 v161, 0x1c0
	v_add_u32_e32 v215, 32, v162
	v_cmp_eq_u32_e32 vcc, 1, v163
	v_cndmask_b32_e32 v215, v162, v215, vcc
	v_mov_b32_e32 v165, s90
	v_mov_b32_e32 v164, 32
	v_cndmask_b32_e32 v165, v165, v164, vcc
	v_cmp_gt_u32_e32 vcc, 32, v162
	v_cndmask_b32_e32 v1, v1, v215, vcc
	v_cndmask_b32_e32 v161, v161, v165, vcc
	v_lshlrev_b32_e32 v164, 10, v1
	s_mov_b64 s[82:83], 0
	v_readlane_b32 s37, v252, 12
	v_readlane_b32 s58, v252, 53
	v_readlane_b32 s59, v252, 54
	v_readlane_b32 s60, v252, 55
	v_readlane_b32 s61, v252, 56
	v_readlane_b32 s62, v252, 57
	v_readlane_b32 s63, v252, 58
	v_readlane_b32 s41, v252, 28
	v_readlane_b32 s42, v252, 29
	v_readlane_b32 s43, v252, 30
	v_readlane_b32 s44, v252, 31
	v_readlane_b32 s45, v252, 32
	v_readlane_b32 s46, v252, 33
	v_readlane_b32 s47, v252, 34
	v_readlane_b32 s48, v252, 35
	v_readlane_b32 s49, v252, 36
	v_readlane_b32 s52, v252, 39
	v_readlane_b32 s53, v252, 40
	v_readlane_b32 s54, v252, 41
	v_readlane_b32 s55, v252, 42
	s_branch .LBB0_897

; DI void phase_m2(const Params& p, int l, int bid, int nb, h16* lds) {
;     ...
;   const int ustep = (bid < 32) ? total : (nb - 32);
;   for (int u = ustart; u < total; u += ustep) {
;     int v = u;
;     if (v >= 5288) { v -= 5288; if (v < nA) conv_one(p, l, 2560 + v, lds); else conv_one(p, l + 1, v - nA, lds); continue; }
.LBB0_896:
	s_or_b64 exec, exec, s[4:5]
	v_add_u32_e32 v1, v1, v161
	v_mov_b32_e32 v215, s90
	v_cmp_le_u32_e32 vcc, 0xa8, v1
	s_mov_b64 s[36:37], vcc
	v_cmp_eq_u32_e32 vcc, 32, v161
	s_and_b64 vcc, vcc, s[36:37]
	v_cndmask_b32_e32 v1, v1, v215, vcc
	v_cmp_le_i32_e32 vcc, s90, v1
	s_or_b64 s[82:83], vcc, s[82:83]
	s_andn2_b64 exec, exec, s[82:83]
	s_cbranch_execz .LBB0_1028

; DI int otid() { int t = threadIdx.x & 255; asm volatile("" : "+v"(t)); return t; }
; DI void dn_c2_unit(const Params& p, int dh, int w) {
;   unsigned char* ws = p.ws;
;   const int tid = otid(), lane = tid & 63;
;   if (tid >= 64) return;
;   const h16* cw = (const h16*)(ws + OFF_CW) + (size_t)dh * 256 * 4096;
;   const h16* ckd = (const h16*)(ws + OFF_CKD) + (size_t)dh * 256 * 4096;
;   const float* cu = (const float*)(ws + OFF_CU) + (size_t)dh * 256 * 4096;
;   const float* cdl = (const float*)(ws + OFF_CDL) + (size_t)dh * 256;
;   h16* cs = (h16*)(ws + OFF_CS) + (size_t)dh * 256 * 4096;
;   h16* cvn = (h16*)(ws + OFF_CVN) + (size_t)dh * 256 * 4096;
;   f4v S[4];
; #pragma unroll
;   for (int i = 0; i < 4; ++i) S[i] = (f4v){0.f, 0.f, 0.f, 0.f};
;   h8v wA[4][2], kA[4][2]; f4v uu[4]; float dl;
; #pragma unroll
;   for (int t = 0; t < 4; ++t) {
; #pragma unroll
;     for (int s = 0; s < 2; ++s) {
;       wA[t][s] = *(const h8v*)&cw[((t * 2 + s) * 64 + lane) * 8];
;       kA[t][s] = *(const h8v*)&ckd[((t * 2 + s) * 64 + lane) * 8];
;     }
;     uu[t] = *(const f4v*)&cu[((w * 4 + t) * 64 + lane) * 4];
;   }
;   dl = cdl[0];
;   for (int n = 0; n < 256; ++n) {
;     h8v wN[4][2], kN[4][2]; f4v uN[4]; float dlN = 0.f;
;     const int nn = (n + 1 < 256) ? n + 1 : n;
;     {
;       const h16* cw1 = cw + (size_t)nn * 4096; const h16* ck1 = ckd + (size_t)nn * 4096; const float* cu1 = cu + (size_t)nn * 4096;
; #pragma unroll
;       for (int t = 0; t < 4; ++t) {
; #pragma unroll
;         for (int s = 0; s < 2; ++s) {
;           wN[t][s] = *(const h8v*)&cw1[((t * 2 + s) * 64 + lane) * 8];
;           kN[t][s] = *(const h8v*)&ck1[((t * 2 + s) * 64 + lane) * 8];
;         }
;         uN[t] = *(const f4v*)&cu1[((w * 4 + t) * 64 + lane) * 4];
;       }
;       dlN = cdl[nn];
.LBB0_953:
	s_andn2_saveexec_b64 s[2:3], s[86:87]
	s_cbranch_execz .LBB0_959
	v_mov_b32_e32 v2, v182
	s_nop 0
	v_cmp_gt_i32_e32 vcc, 64, v2
	s_and_saveexec_b64 s[4:5], vcc
	s_cbranch_execz .LBB0_958
	v_ashrrev_i32_e32 v78, 2, v1
	v_ashrrev_i32_e32 v79, 31, v78
	v_readlane_b32 s6, v254, 23
	v_lshlrev_b64 v[150:151], 22, v[78:79]
	v_readlane_b32 s7, v254, 24
	v_and_b32_e32 v86, 63, v2
	v_lshlrev_b64 v[152:153], 21, v[78:79]
	v_lshl_add_u64 v[2:3], s[6:7], 0, v[150:151]
	v_readlane_b32 s6, v254, 21
	v_readlane_b32 s7, v254, 22
	v_lshlrev_b32_e32 v82, 4, v86
	v_mov_b32_e32 v83, v0
	v_lshl_add_u64 v[10:11], s[6:7], 0, v[152:153]
	v_readlane_b32 s6, v254, 25
	v_readlane_b32 s7, v254, 26
	v_lshlrev_b32_e32 v8, 10, v1
	v_lshl_add_u64 v[4:5], v[10:11], 0, v[82:83]
	v_lshl_add_u64 v[12:13], s[6:7], 0, v[152:153]
	v_lshl_add_u64 v[6:7], v[12:13], 0, v[82:83]
	v_and_b32_e32 v171, 0xc00, v8
	v_lshlrev_b32_e32 v83, 2, v86
	v_or_b32_e32 v8, v83, v171
	v_lshlrev_b32_e32 v8, 2, v8
	v_mov_b32_e32 v9, v0
	global_load_dwordx4 v[50:53], v[4:5], off
	global_load_dwordx4 v[18:21], v[4:5], off offset:1024
	global_load_dwordx4 v[70:73], v[6:7], off
	global_load_dwordx4 v[14:17], v[6:7], off offset:1024
	v_lshl_add_u64 v[84:85], v[2:3], 0, v[8:9]
	s_mov_b64 s[38:39], 0x2000
	v_lshl_add_u64 v[234:235], v[4:5], 0, s[38:39]
	v_lshl_add_u64 v[238:239], v[6:7], 0, s[38:39]
	s_mov_b64 s[40:41], 0x3000
	v_lshl_add_u64 v[236:237], v[4:5], 0, s[40:41]
	v_lshl_add_u64 v[240:241], v[6:7], 0, s[40:41]
	s_mov_b64 s[40:41], 0x4000
	v_lshl_add_u64 v[242:243], v[84:85], 0, s[40:41]
	global_load_dwordx4 v[26:29], v[4:5], off offset:2048
	global_load_dwordx4 v[22:25], v[4:5], off offset:3072
	global_load_dwordx4 v[38:41], v[6:7], off offset:2048
	s_nop 0
	global_load_dwordx4 v[2:5], v[6:7], off offset:3072
	global_load_dwordx4 v[58:61], v[84:85], off
	global_load_dwordx4 v[54:57], v[84:85], off offset:1024
	v_or_b32_e32 v6, 0x1000, v82
	v_mov_b32_e32 v7, v0
	v_lshl_add_u64 v[8:9], v[10:11], 0, v[6:7]
	v_lshl_add_u64 v[6:7], v[12:13], 0, v[6:7]
	global_load_dwordx4 v[34:37], v[8:9], off
	global_load_dwordx4 v[30:33], v[6:7], off
	v_or_b32_e32 v6, 0x1400, v82
	v_mov_b32_e32 v7, v0
	v_or_b32_e32 v42, 0x1800, v82
	v_mov_b32_e32 v43, v0
	v_or_b32_e32 v66, 0x1c00, v82
	v_mov_b32_e32 v67, v0
	v_lshl_add_u64 v[8:9], v[10:11], 0, v[6:7]
	v_lshl_add_u64 v[6:7], v[12:13], 0, v[6:7]
	v_lshl_add_u64 v[44:45], v[10:11], 0, v[42:43]
	v_lshl_add_u64 v[42:43], v[12:13], 0, v[42:43]
	v_lshl_add_u64 v[10:11], v[10:11], 0, v[66:67]
	v_lshl_add_u64 v[12:13], v[12:13], 0, v[66:67]
	v_readlane_b32 s6, v254, 19
	v_lshlrev_b64 v[80:81], 10, v[78:79]
	global_load_dwordx4 v[46:49], v[8:9], off
	s_nop 0
	global_load_dwordx4 v[6:9], v[6:7], off
	s_nop 0
	global_load_dwordx4 v[62:65], v[44:45], off
	s_nop 0
	global_load_dwordx4 v[42:45], v[42:43], off
	s_nop 0
	global_load_dwordx4 v[66:69], v[10:11], off
	s_nop 0
	global_load_dwordx4 v[10:13], v[12:13], off
	s_nop 0
	global_load_dwordx4 v[74:77], v[84:85], off offset:2048
	global_load_dwordx4 v[90:93], v[84:85], off offset:3072
	v_readlane_b32 s7, v254, 20
	v_lshlrev_b32_e32 v174, 3, v86
	v_lshlrev_b64 v[154:155], 20, v[78:79]
	v_lshl_add_u64 v[84:85], s[6:7], 0, v[80:81]
	v_lshl_add_u64 v[244:245], v[84:85], 0, 4
	global_load_dword v160, v[84:85], off
	v_and_b32_e32 v84, 0xc00, v164
	v_or_b32_e32 v78, v84, v174
	v_lshl_or_b32 v158, v78, 1, v152
	v_or_b32_e32 v78, v84, v83
	v_readlane_b32 s16, v252, 3
	s_mov_b64 s[6:7], 0x1df08004
	v_lshl_or_b32 v150, v78, 2, v150
	v_mov_b32_e32 v78, 0
	v_readlane_b32 s17, v252, 4
	v_lshl_add_u64 v[156:157], v[80:81], 0, s[6:7]
	v_mov_b32_e32 v159, v153
	v_or_b32_e32 v152, v152, v82
	s_movk_i32 s6, 0xff
	v_mov_b32_e32 v79, v78
	v_mov_b32_e32 v80, v78
	v_mov_b32_e32 v81, v78
	v_mov_b32_e32 v94, v78
	v_mov_b32_e32 v95, v78
	v_mov_b32_e32 v96, v78
	v_mov_b32_e32 v97, v78
	v_mov_b32_e32 v86, v78
	v_mov_b32_e32 v87, v78
	v_mov_b32_e32 v88, v78
	v_mov_b32_e32 v89, v78
	v_mov_b32_e32 v82, v78
	v_mov_b32_e32 v83, v78
	v_mov_b32_e32 v84, v78
	v_mov_b32_e32 v85, v78
	v_readlane_b32 s20, v252, 7
	v_readlane_b32 s21, v252, 8
	s_mov_b64 s[16:17], 0x2000
	v_readlane_b32 s18, v252, 5
	v_readlane_b32 s19, v252, 6
	v_readlane_b32 s22, v252, 9
	v_readlane_b32 s23, v252, 10
	v_readfirstlane_b32 s37, v183
	v_and_b32_e32 v247, 63, v182
	v_lshlrev_b32_e32 v247, 4, v247
	s_mov_b32 s37, 16
	s_movk_i32 s42, 0x5410
	s_mov_b32 s43, 0x1c810
	s_mov_b32 s34, s42
	s_waitcnt vmcnt(21)
; DI void dn_c2_unit(const Params& p, int dh, int w) {
;     ...
;   for (int n = 0; n < 256; ++n) {
;     h8v wN[4][2], kN[4][2]; f4v uN[4]; float dlN = 0.f;
;     const int nn = (n + 1 < 256) ? n + 1 : n;
;     {
;       const h16* cw1 = cw + (size_t)nn * 4096; const h16* ck1 = ckd + (size_t)nn * 4096; const float* cu1 = cu + (size_t)nn * 4096;
; #pragma unroll
;       for (int t = 0; t < 4; ++t) {
; #pragma unroll
;         for (int s = 0; s < 2; ++s) {
;           wN[t][s] = *(const h8v*)&cw1[((t * 2 + s) * 64 + lane) * 8];
;           kN[t][s] = *(const h8v*)&ck1[((t * 2 + s) * 64 + lane) * 8];
;         }
;         uN[t] = *(const f4v*)&cu1[((w * 4 + t) * 64 + lane) * 4];
;       }
;       dlN = cdl[nn];
;     }
	s_mov_b32 m0, s34
	s_nop 0
	global_load_lds_dwordx4 v[234:235], off
	global_load_lds_dwordx4 v[234:235], off offset:1024
	global_load_lds_dwordx4 v[234:235], off offset:2048
	global_load_lds_dwordx4 v[234:235], off offset:3072
	s_add_u32 m0, s34, 0x1000
	s_nop 0
	global_load_lds_dwordx4 v[236:237], off
	global_load_lds_dwordx4 v[236:237], off offset:1024
	global_load_lds_dwordx4 v[236:237], off offset:2048
	global_load_lds_dwordx4 v[236:237], off offset:3072
	s_add_u32 m0, s34, 0x2000
	s_nop 0
	global_load_lds_dwordx4 v[238:239], off
	global_load_lds_dwordx4 v[238:239], off offset:1024
	global_load_lds_dwordx4 v[238:239], off offset:2048
	global_load_lds_dwordx4 v[238:239], off offset:3072
	s_add_u32 m0, s34, 0x3000
	s_nop 0
	global_load_lds_dwordx4 v[240:241], off
	global_load_lds_dwordx4 v[240:241], off offset:1024
	global_load_lds_dwordx4 v[240:241], off offset:2048
	global_load_lds_dwordx4 v[240:241], off offset:3072
	s_add_u32 m0, s34, 0x4000
	s_nop 0
	global_load_lds_dwordx4 v[242:243], off
	global_load_lds_dwordx4 v[242:243], off offset:1024
	global_load_lds_dwordx4 v[242:243], off offset:2048
	global_load_lds_dwordx4 v[242:243], off offset:3072
	s_add_u32 m0, s34, 0x5000
	s_nop 0
	global_load_lds_dword v[244:245], off
	v_lshl_add_u64 v[234:235], v[234:235], 0, s[38:39]
	v_lshl_add_u64 v[236:237], v[236:237], 0, s[38:39]
	v_lshl_add_u64 v[238:239], v[238:239], 0, s[38:39]
	v_lshl_add_u64 v[240:241], v[240:241], 0, s[38:39]
	v_lshl_add_u64 v[242:243], v[242:243], 0, s[40:41]
	v_lshl_add_u64 v[244:245], v[244:245], 0, 4
	s_mov_b32 s34, s43
	s_mov_b32 m0, s34
	s_nop 0
	global_load_lds_dwordx4 v[234:235], off
	global_load_lds_dwordx4 v[234:235], off offset:1024
	global_load_lds_dwordx4 v[234:235], off offset:2048
	global_load_lds_dwordx4 v[234:235], off offset:3072
	s_add_u32 m0, s34, 0x1000
	s_nop 0
	global_load_lds_dwordx4 v[236:237], off
	global_load_lds_dwordx4 v[236:237], off offset:1024
	global_load_lds_dwordx4 v[236:237], off offset:2048
	global_load_lds_dwordx4 v[236:237], off offset:3072
	s_add_u32 m0, s34, 0x2000
	s_nop 0
	global_load_lds_dwordx4 v[238:239], off
	global_load_lds_dwordx4 v[238:239], off offset:1024
	global_load_lds_dwordx4 v[238:239], off offset:2048
	global_load_lds_dwordx4 v[238:239], off offset:3072
	s_add_u32 m0, s34, 0x3000
	s_nop 0
	global_load_lds_dwordx4 v[240:241], off
	global_load_lds_dwordx4 v[240:241], off offset:1024
	global_load_lds_dwordx4 v[240:241], off offset:2048
	global_load_lds_dwordx4 v[240:241], off offset:3072
	s_add_u32 m0, s34, 0x4000
	s_nop 0
	global_load_lds_dwordx4 v[242:243], off
	global_load_lds_dwordx4 v[242:243], off offset:1024
	global_load_lds_dwordx4 v[242:243], off offset:2048
	global_load_lds_dwordx4 v[242:243], off offset:3072
	s_add_u32 m0, s34, 0x5000
	s_nop 0
	global_load_lds_dword v[244:245], off
	v_lshl_add_u64 v[234:235], v[234:235], 0, s[38:39]
	v_lshl_add_u64 v[236:237], v[236:237], 0, s[38:39]
	v_lshl_add_u64 v[238:239], v[238:239], 0, s[38:39]
	v_lshl_add_u64 v[240:241], v[240:241], 0, s[38:39]
	v_lshl_add_u64 v[242:243], v[242:243], 0, s[40:41]
	v_lshl_add_u64 v[244:245], v[244:245], 0, 4
	s_mov_b32 s34, s37
	s_add_u32 s35, s37, 0x5400
	s_waitcnt vmcnt(42)

; DI f4v mfma16(h8v a, h8v b, f4v c) { return __builtin_amdgcn_mfma_f32_16x16x32_f16(a, b, c, 0, 0, 0); }
; DI void dn_c2_unit(const Params& p, int dh, int w) {
;     ...
;   for (int n = 0; n < 256; ++n) {
;     h8v wN[4][2], kN[4][2]; f4v uN[4]; float dlN = 0.f;
;     const int nn = (n + 1 < 256) ? n + 1 : n;
;     {
;       const h16* cw1 = cw + (size_t)nn * 4096; const h16* ck1 = ckd + (size_t)nn * 4096; const float* cu1 = cu + (size_t)nn * 4096;
; #pragma unroll
;       for (int t = 0; t < 4; ++t) {
; #pragma unroll
;         for (int s = 0; s < 2; ++s) {
;           wN[t][s] = *(const h8v*)&cw1[((t * 2 + s) * 64 + lane) * 8];
;           kN[t][s] = *(const h8v*)&ck1[((t * 2 + s) * 64 + lane) * 8];
;         }
;         uN[t] = *(const f4v*)&cu1[((w * 4 + t) * 64 + lane) * 4];
;       }
;       dlN = cdl[nn];
;     }
;     h8v Sb[2];
;     Sb[0] = pack8(S[0], S[1]); Sb[1] = pack8(S[2], S[3]);
;     h16* cs1 = cs + (size_t)n * 4096; h16* cv1 = cvn + (size_t)n * 4096;
;     *(h8v*)&cs1[((w * 2 + 0) * 64 + lane) * 8] = Sb[0];
;     *(h8v*)&cs1[((w * 2 + 1) * 64 + lane) * 8] = Sb[1];
;     f4v vn[4];
; #pragma unroll
;     for (int t = 0; t < 4; ++t) { vn[t] = uu[t]; vn[t] = mfma16(wA[t][0], Sb[0], vn[t]); vn[t] = mfma16(wA[t][1], Sb[1], vn[t]); }
;     h8v Vb[2];
;     Vb[0] = pack8(vn[0], vn[1]); Vb[1] = pack8(vn[2], vn[3]);
;     *(h8v*)&cv1[((w * 2 + 0) * 64 + lane) * 8] = Vb[0];
;     *(h8v*)&cv1[((w * 2 + 1) * 64 + lane) * 8] = Vb[1];
; #pragma unroll
;     for (int t = 0; t < 4; ++t) { S[t] *= dl; S[t] = mfma16(kA[t][0], Vb[0], S[t]); S[t] = mfma16(kA[t][1], Vb[1], S[t]); }
; #pragma unroll
;     for (int t = 0; t < 4; ++t) { wA[t][0] = wN[t][0]; wA[t][1] = wN[t][1]; kA[t][0] = kN[t][0]; kA[t][1] = kN[t][1]; uu[t] = uN[t]; }
;     dl = dlN;
;   }
.Lscan_wait_done:
	global_load_lds_dwordx4 v[240:241], off offset:1024
	global_load_lds_dwordx4 v[240:241], off offset:2048
	global_load_lds_dwordx4 v[240:241], off offset:3072
	s_add_u32 m0, s34, 0x4000
	s_nop 0
	global_load_lds_dwordx4 v[242:243], off
	global_load_lds_dwordx4 v[242:243], off offset:1024
	global_load_lds_dwordx4 v[242:243], off offset:2048
	global_load_lds_dwordx4 v[242:243], off offset:3072
	s_add_u32 m0, s34, 0x5000
	s_nop 0
	global_load_lds_dword v[244:245], off
	v_lshl_add_u64 v[234:235], v[234:235], 0, s[38:39]
	v_lshl_add_u64 v[236:237], v[236:237], 0, s[38:39]
	v_lshl_add_u64 v[238:239], v[238:239], 0, s[38:39]
	v_lshl_add_u64 v[240:241], v[240:241], 0, s[38:39]
	v_lshl_add_u64 v[242:243], v[242:243], 0, s[40:41]
	v_lshl_add_u64 v[244:245], v[244:245], 0, 4
	v_add_u32_e32 v246, s35, v247
	v_mov_b32_e32 v248, s35
	s_cmp_eq_u32 s34, s37
	s_cselect_b32 s36, s42, s43
	s_cmp_eq_u32 s34, s43
	s_cselect_b32 s34, s37, s36
	s_cmp_eq_u32 s35, s37
	s_cselect_b32 s36, s42, s43
	s_cmp_eq_u32 s35, s43
	s_cselect_b32 s35, s37, s36
	v_mov_b64_e32 v[178:179], v[20:21]
	v_mov_b64_e32 v[176:177], v[18:19]
	v_mov_b64_e32 v[148:149], v[24:25]
	v_mov_b64_e32 v[146:147], v[22:23]
	s_nop 0
	v_mov_b64_e32 v[132:133], v[28:29]
	v_mov_b64_e32 v[140:141], v[36:37]
	v_mov_b64_e32 v[130:131], v[26:27]
	v_mov_b64_e32 v[138:139], v[34:35]
	v_mov_b64_e32 v[218:219], v[64:65]
	v_mov_b64_e32 v[216:217], v[62:63]
	v_mov_b64_e32 v[120:121], v[60:61]
	v_mov_b64_e32 v[128:129], v[56:57]
	v_mov_b64_e32 v[118:119], v[58:59]
	v_mov_b64_e32 v[126:127], v[54:55]
	v_mov_b64_e32 v[144:145], v[48:49]
	v_cvt_pk_f16_f32 v101, v96, v97
	v_cvt_pk_f16_f32 v100, v94, v95
	v_cvt_pk_f16_f32 v99, v80, v81
	v_cvt_pk_f16_f32 v98, v78, v79
	v_mov_b64_e32 v[142:143], v[46:47]
	v_mov_b64_e32 v[136:137], v[68:69]
	ds_read_b128 v[18:21], v246 offset:1024
	ds_read_b128 v[26:29], v246 offset:2048
	ds_read_b128 v[106:109], v246 offset:9216
	s_nop 0
	ds_read_b128 v[22:25], v246 offset:3072
	s_nop 0
	ds_read_b128 v[110:113], v246 offset:10240
	ds_read_b128 v[114:117], v246 offset:11264
	ds_read_b128 v[58:61], v246 offset:16384
	ds_read_b128 v[54:57], v246 offset:17408
	v_mfma_f32_16x16x32_f16 v[220:223], v[50:53], v[98:101], v[118:121]
	ds_read_b128 v[34:37], v246 offset:4096
	s_nop 1
	ds_read_b128 v[118:121], v246 offset:8192
	ds_read_b128 v[122:125], v246 offset:12288
	v_mov_b64_e32 v[134:135], v[66:67]
	v_mfma_f32_16x16x32_f16 v[224:227], v[130:133], v[98:101], v[126:129]
	ds_read_b128 v[46:49], v246 offset:5120
	s_nop 1
	ds_read_b128 v[126:129], v246 offset:13312
	ds_read_b128 v[130:133], v246 offset:15360
	v_cvt_pk_f16_f32 v105, v84, v85
	v_cvt_pk_f16_f32 v104, v82, v83
	v_mfma_f32_16x16x32_f16 v[228:231], v[138:141], v[98:101], v[74:77]
	ds_read_b128 v[138:141], v246 offset:14336
	s_nop 1
	ds_read_b128 v[74:77], v246 offset:18432
	ds_read_b128 v[62:65], v246 offset:6144
	ds_read_b128 v[66:69], v246 offset:7168
	ds_read_b128 v[50:53], v246
	ds_read_b32 v175, v248 offset:20480
	v_cvt_pk_f16_f32 v103, v88, v89
	v_mfma_f32_16x16x32_f16 v[216:219], v[216:219], v[98:101], v[90:93]
	v_cvt_pk_f16_f32 v102, v86, v87
	v_pk_mul_f32 v[80:81], v[160:161], v[80:81] op_sel_hi:[0,1]
	v_pk_mul_f32 v[78:79], v[160:161], v[78:79] op_sel_hi:[0,1]
	ds_read_b128 v[90:93], v246 offset:19456
	v_mfma_f32_16x16x32_f16 v[176:179], v[176:179], v[102:105], v[220:223]
	v_mul_f32_e64 v96, v160, v96
	v_mul_f32_e64 v97, v160, v97
	v_pk_mul_f32 v[94:95], v[160:161], v[94:95] op_sel_hi:[0,1]
	v_pk_mul_f32 v[88:89], v[160:161], v[88:89] op_sel_hi:[0,1]
	v_mfma_f32_16x16x32_f16 v[146:149], v[146:149], v[102:105], v[224:227]
	v_mul_f32_e64 v86, v160, v86
	v_mul_f32_e64 v87, v160, v87
	v_pk_mul_f32 v[84:85], v[160:161], v[84:85] op_sel_hi:[0,1]
	v_pk_mul_f32 v[82:83], v[160:161], v[82:83] op_sel_hi:[0,1]
	v_mfma_f32_16x16x32_f16 v[142:145], v[142:145], v[102:105], v[228:231]
	v_lshl_add_u64 v[200:201], s[20:21], 0, v[158:159]
	s_nop 1
	v_cvt_pk_f16_f32 v149, v148, v149
	v_cvt_pk_f16_f32 v148, v146, v147
	v_mfma_f32_16x16x32_f16 v[134:137], v[134:137], v[102:105], v[216:219]
	v_cvt_pk_f16_f32 v147, v178, v179
	v_cvt_pk_f16_f32 v146, v176, v177
	s_mov_b32 s7, 0x1df0a000
	v_add_co_u32_e32 v176, vcc, s7, v200
	v_mfma_f32_16x16x32_f16 v[70:73], v[70:73], v[146:149], v[78:81]
	s_nop 2
	v_cvt_pk_f16_f32 v137, v136, v137
	v_cvt_pk_f16_f32 v136, v134, v135
	v_cvt_pk_f16_f32 v135, v144, v145
	v_mfma_f32_16x16x32_f16 v[38:41], v[38:41], v[146:149], v[94:97]
	v_cvt_pk_f16_f32 v134, v142, v143
	v_addc_co_u32_e32 v177, vcc, 0, v201, vcc
	v_mfma_f32_16x16x32_f16 v[30:33], v[30:33], v[146:149], v[86:89]
	s_mov_b32 s7, 0x1ef0a000
	s_add_i32 s6, s6, -1
	s_mov_b64 s[8:9], 0x4000
	v_mfma_f32_16x16x32_f16 v[42:45], v[42:45], v[146:149], v[82:85]
	global_store_dwordx4 v[176:177], v[98:101], off
	v_lshl_add_u64 v[156:157], v[156:157], 0, 4
	v_lshl_add_u64 v[158:159], v[158:159], 0, s[16:17]
	v_mfma_f32_16x16x32_f16 v[78:81], v[14:17], v[134:137], v[70:73]
	v_add_co_u32_e32 v14, vcc, s7, v200
	v_lshl_add_u64 v[150:151], v[150:151], 0, s[8:9]
	v_mfma_f32_16x16x32_f16 v[94:97], v[2:5], v[134:137], v[38:41]
	v_addc_co_u32_e32 v15, vcc, 0, v201, vcc
	global_store_dwordx4 v[176:177], v[102:105], off offset:1024
	global_store_dwordx4 v[14:15], v[146:149], off
	global_store_dwordx4 v[14:15], v[134:137], off offset:1024
	v_mfma_f32_16x16x32_f16 v[86:89], v[6:9], v[134:137], v[30:33]
	v_lshl_add_u64 v[152:153], v[152:153], 0, s[16:17]
	s_cmp_eq_u32 s6, 0
	s_waitcnt lgkmcnt(0)
	v_mov_b64_e32 v[14:15], v[106:107]
	v_mfma_f32_16x16x32_f16 v[82:85], v[10:13], v[134:137], v[42:45]
	v_mov_b64_e32 v[38:39], v[110:111]
	v_mov_b64_e32 v[2:3], v[114:115]
	v_mov_b64_e32 v[4:5], v[116:117]
	v_mov_b64_e32 v[40:41], v[112:113]
	v_mov_b64_e32 v[70:71], v[118:119]
	v_mov_b64_e32 v[30:31], v[122:123]
	v_mov_b64_e32 v[32:33], v[124:125]
	v_mov_b64_e32 v[16:17], v[108:109]
	v_mov_b64_e32 v[6:7], v[126:127]
	v_mov_b64_e32 v[10:11], v[130:131]
	v_mov_b64_e32 v[12:13], v[132:133]
	v_mov_b64_e32 v[42:43], v[138:139]
	v_mov_b64_e32 v[44:45], v[140:141]
	v_mov_b64_e32 v[8:9], v[128:129]
	v_mov_b64_e32 v[72:73], v[120:121]
	v_mov_b32_e32 v160, v175
	s_cbranch_scc0 .LBB0_956
; DI f4v mfma16(h8v a, h8v b, f4v c) { return __builtin_amdgcn_mfma_f32_16x16x32_f16(a, b, c, 0, 0, 0); }
; DI void dn_c2_unit(const Params& p, int dh, int w) {
;     ...
;     h8v Sb[2];
;     Sb[0] = pack8(S[0], S[1]); Sb[1] = pack8(S[2], S[3]);
;     h16* cs1 = cs + (size_t)n * 4096; h16* cv1 = cvn + (size_t)n * 4096;
;     *(h8v*)&cs1[((w * 2 + 0) * 64 + lane) * 8] = Sb[0];
;     *(h8v*)&cs1[((w * 2 + 1) * 64 + lane) * 8] = Sb[1];
;     f4v vn[4];
; #pragma unroll
;     for (int t = 0; t < 4; ++t) { vn[t] = uu[t]; vn[t] = mfma16(wA[t][0], Sb[0], vn[t]); vn[t] = mfma16(wA[t][1], Sb[1], vn[t]); }
;     h8v Vb[2];
;     Vb[0] = pack8(vn[0], vn[1]); Vb[1] = pack8(vn[2], vn[3]);
;     *(h8v*)&cv1[((w * 2 + 0) * 64 + lane) * 8] = Vb[0];
;     *(h8v*)&cv1[((w * 2 + 1) * 64 + lane) * 8] = Vb[1];
; #pragma unroll
;     for (int t = 0; t < 4; ++t) { S[t] *= dl; S[t] = mfma16(kA[t][0], Vb[0], S[t]); S[t] = mfma16(kA[t][1], Vb[1], S[t]); }
	v_cvt_pk_f16_f32 v5, v96, v97
	v_cvt_pk_f16_f32 v4, v94, v95
	v_cvt_pk_f16_f32 v3, v80, v81
	v_cvt_pk_f16_f32 v2, v78, v79
	v_cvt_pk_f16_f32 v9, v84, v85
	v_cvt_pk_f16_f32 v8, v82, v83
	v_mfma_f32_16x16x32_f16 v[10:13], v[50:53], v[2:5], v[58:61]
	v_cvt_pk_f16_f32 v7, v88, v89
	v_cvt_pk_f16_f32 v6, v86, v87
	v_readlane_b32 s6, v254, 36
	v_mfma_f32_16x16x32_f16 v[14:17], v[26:29], v[2:5], v[54:57]
	v_readlane_b32 s7, v254, 37
	v_mfma_f32_16x16x32_f16 v[10:13], v[18:21], v[6:9], v[10:13]
	v_lshlrev_b64 v[18:19], 1, v[154:155]
	v_lshl_add_u64 v[20:21], s[6:7], 0, v[18:19]
	v_readlane_b32 s6, v254, 38
	v_readlane_b32 s7, v254, 39
	v_mfma_f32_16x16x32_f16 v[14:17], v[22:25], v[6:9], v[14:17]
	v_mov_b32_e32 v23, v0
	v_lshl_add_u64 v[26:27], s[6:7], 0, v[18:19]
	v_or_b32_e32 v18, v174, v171
	s_mov_b64 s[6:7], 0x1fe000
	v_lshlrev_b32_e32 v22, 1, v18
	v_lshl_add_u64 v[24:25], v[20:21], 0, s[6:7]
	v_lshl_add_u64 v[28:29], v[24:25], 0, v[22:23]
	v_mfma_f32_16x16x32_f16 v[18:21], v[34:37], v[2:5], v[74:77]
	global_store_dwordx4 v[28:29], v[2:5], off
	v_or_b32_e32 v28, 0x400, v22
	v_mov_b32_e32 v29, v0
	s_waitcnt vmcnt(5)
	v_mfma_f32_16x16x32_f16 v[2:5], v[62:65], v[2:5], v[90:93]
	v_lshl_add_u64 v[24:25], v[24:25], 0, v[28:29]
	global_store_dwordx4 v[24:25], v[6:9], off
	v_lshl_add_u64 v[24:25], v[26:27], 0, s[6:7]
	v_mfma_f32_16x16x32_f16 v[18:21], v[46:49], v[6:9], v[18:21]
	v_cvt_pk_f16_f32 v17, v16, v17
	v_cvt_pk_f16_f32 v16, v14, v15
	v_cvt_pk_f16_f32 v15, v12, v13
	v_mfma_f32_16x16x32_f16 v[2:5], v[66:69], v[6:9], v[2:5]
	v_cvt_pk_f16_f32 v14, v10, v11
	v_lshl_add_u64 v[6:7], v[24:25], 0, v[22:23]
	global_store_dwordx4 v[6:7], v[14:17], off
	v_lshl_add_u64 v[6:7], v[24:25], 0, v[28:29]
	s_nop 3
	v_cvt_pk_f16_f32 v5, v4, v5
	v_cvt_pk_f16_f32 v4, v2, v3
	v_cvt_pk_f16_f32 v3, v20, v21
	v_cvt_pk_f16_f32 v2, v18, v19
	global_store_dwordx4 v[6:7], v[2:5], off
	s_waitcnt vmcnt(0)
